# conversion for w_up, w_out and a quarter of w_down moved to the START of P1 in the workgroups with one in-proj unit fewer (de-synchronises the two workgroup classes); remaining w_down converted in P2
# speedup vs baseline: 1.0195x; 1.0026x over previous
; #define LAS __attribute__((address_space(3)))
; __global__ void __launch_bounds__(NT, 2) fwd_mega(Args A) {
;     ...
;         constexpr int NU = (T / 256) * (INW / 256);
;         const int rem = NU % G, NH = (rem == 0) ? G : G - rem, hi = (rem == 0) ? cid : cid - rem;
;         if (hi >= 0) {
;             constexpr int I_UP = (D / 64) * (FF / 64);
;             LAS float* scr = (LAS float*)(lds + wave * 16640);
;             for (int it = hi * NW + wave; it < I_UP; it += NH * NW) transpose_tile(A.w_up, D, FF, WupT, A.g_ffn, A.g_ffn, D, scr, it, lane);
;         }
.LBB0_226:
	s_abs_i32 s0, s30
	v_cvt_f32_u32_e32 v0, s0
	s_sub_i32 s1, 0, s0
	v_rcp_iflag_f32_e32 v0, v0
	s_nop 0
	v_mul_f32_e32 v0, 0x4f7ffffe, v0
	v_cvt_u32_f32_e32 v0, v0
	s_nop 0
	v_readfirstlane_b32 s2, v0
	s_mul_i32 s1, s1, s2
	s_mul_hi_u32 s1, s2, s1
	s_add_i32 s2, s2, s1
	s_mul_hi_u32 s1, s2, 0x380
	s_mul_i32 s1, s1, s0
	s_sub_i32 s1, 0x380, s1
	s_sub_i32 s2, s1, s0
	s_cmp_ge_u32 s1, s0
	s_cselect_b32 s1, s2, s1
	s_sub_i32 s2, s1, s0
	s_cmp_ge_u32 s1, s0
	s_cselect_b32 s1, s2, s1
	s_sub_i32 s0, s12, s1
	s_cmp_lt_i32 s0, 0
	s_cbranch_scc1 .Lcvb_skip
	s_lshl_b32 s0, s0, 3
	v_readlane_b32 s2, v255, 3
	s_sub_i32 s4, s30, s1
	s_nop 1
	s_add_i32 s60, s0, s2
	s_lshl_b32 s61, s4, 3
	s_movk_i32 s62, 0x1800
	s_cmp_ge_u32 s60, s62
	s_cbranch_scc1 .Lcvb_end
	v_readlane_b32 s63, v255, 3
	v_and_b32_e32 v122, 63, v160
	v_and_b32_e32 v112, 15, v122
	v_lshlrev_b32_e32 v112, 4, v112
	v_lshrrev_b32_e32 v113, 4, v122
	v_lshlrev_b32_e32 v114, 2, v113
	v_and_b32_e32 v115, 7, v122
	v_lshrrev_b32_e32 v116, 3, v122
	s_mulk_i32 s63, 0x4100
	s_movk_i32 s80, 0x104
	v_mad_u32_u24 v117, v113, s80, v112
	v_add_u32_e32 v117, s63, v117
	s_movk_i32 s80, 0x820
	v_lshlrev_b32_e32 v119, 2, v116
	v_mad_u32_u24 v118, v115, s80, v119
	v_add_u32_e32 v118, s63, v118
	v_add_u32_e32 v119, 0x400, v118
	v_lshlrev_b32_e32 v115, 4, v115
	s_mov_b32 s75, s60
	s_cmp_lt_u32 s75, 0x1000
	s_cbranch_scc1 .Lcvb_p0_m0
	s_cmp_lt_u32 s75, 0x1400
	s_cbranch_scc1 .Lcvb_p0_m1
	s_branch .Lcvb_p0_m2

; #define LAS __attribute__((address_space(3)))
; __global__ void __launch_bounds__(NT, 2) fwd_mega(Args A) {
;     ...
;             LAS float* scr = (LAS float*)(lds + wave * 16640);
;             for (int it = hi * NW + wave; it < I_UP; it += NH * NW) transpose_tile(A.w_up, D, FF, WupT, A.g_ffn, A.g_ffn, D, scr, it, lane);
;         }
.Lcvb_fin:
.Lcvb_end:
	s_waitcnt lgkmcnt(0)
	s_barrier

; __global__ void __launch_bounds__(NT, 2) fwd_mega(Args A) {
;     ...
;         constexpr int NU = (T / 256) * (INW / 256);
;         const int rem = NU % G, NH = (rem == 0) ? G : G - rem, hi = (rem == 0) ? cid : cid - rem;
;         if (hi >= 0) {
.LBB0_464:
	s_add_u32 s8, s28, 0x1900000
	s_addc_u32 s9, s29, 0
	s_abs_i32 s0, s30
	v_cvt_f32_u32_e32 v0, s0
	s_sub_i32 s1, 0, s0
	v_rcp_iflag_f32_e32 v0, v0
	s_nop 0
	v_mul_f32_e32 v0, 0x4f7ffffe, v0
	v_cvt_u32_f32_e32 v0, v0
	s_nop 0
	v_readfirstlane_b32 s2, v0
	s_mul_i32 s1, s1, s2
	s_mul_hi_u32 s1, s2, s1
	s_add_i32 s2, s2, s1
	s_mul_hi_u32 s1, s2, 0x380
	s_mul_i32 s1, s1, s0
	s_sub_i32 s1, 0x380, s1
	s_sub_i32 s2, s1, s0
	s_cmp_ge_u32 s1, s0
	s_cselect_b32 s1, s2, s1
	s_sub_i32 s2, s1, s0
	s_cmp_ge_u32 s1, s0
	s_cselect_b32 s1, s2, s1
	s_sub_i32 s0, s12, s1
	s_cmp_lt_i32 s0, 0
	s_cbranch_scc1 .LBB0_501
.LBB0_500:
	v_readlane_b32 s88, v255, 1
	v_readlane_b32 s89, v255, 2

; #define LAS __attribute__((address_space(3)))
; __device__ __forceinline__ void convert_out_down(const Args& A, LAS unsigned char* lds, int vcu, int G) {
;     int tid = threadIdx.x; asm volatile("" : "+v"(tid)); const int lane = tid & 63, wave = __builtin_amdgcn_readfirstlane(tid >> 6);
;     unsigned char* ws = A.ws;
;     __syncthreads();
;     LAS float* scr = (LAS float*)(lds + wave * 16640);
;     constexpr int I_OUT0 = (D / 64) * (D / 64), I_DN0 = (FF / 64) * (D / 64);
;     for (int it = vcu * NW + wave; it < I_OUT0 + I_DN0; it += G * NW) {
;         if (it < I_OUT0) transpose_tile(A.w_out, D, D, (bf16*)(ws + WS_WOUT), A.g_ao, A.g_go, 1024, scr, it, lane);
;         else transpose_tile(A.w_down, FF, D, (bf16*)(ws + WS_WDOWN), nullptr, nullptr, 0, scr, it - I_OUT0, lane);
;     }
;     __syncthreads();
.LBB0_553:
	s_or_b64 exec, exec, s[2:3]
	s_add_u32 s6, s28, 0x1100000
	s_addc_u32 s7, s29, 0
	s_bitcmp1_b32 s96, 0
	s_cselect_b64 s[22:23], -1, 0
	s_and_b64 vcc, exec, s[22:23]
	s_waitcnt lgkmcnt(0)
	s_barrier
	s_cbranch_vccnz .LBB0_594
	s_lshl_b32 s0, s96, 3
	v_readlane_b32 s2, v255, 3
	s_nop 3
	s_add_i32 s60, s0, s2
	s_mov_b32 s61, s52
	s_movk_i32 s62, 0xc00
	s_cmp_ge_u32 s60, s62
	s_cbranch_scc1 .Lcvc_end
	v_readlane_b32 s63, v255, 3
	v_and_b32_e32 v122, 63, v160
	v_and_b32_e32 v112, 15, v122
	v_lshlrev_b32_e32 v112, 4, v112
	v_lshrrev_b32_e32 v113, 4, v122
	v_lshlrev_b32_e32 v114, 2, v113
	v_and_b32_e32 v115, 7, v122
	v_lshrrev_b32_e32 v116, 3, v122
	s_mulk_i32 s63, 0x4100
	s_movk_i32 s80, 0x104
	v_mad_u32_u24 v117, v113, s80, v112
	v_add_u32_e32 v117, s63, v117
	s_movk_i32 s80, 0x820
	v_lshlrev_b32_e32 v119, 2, v116
	v_mad_u32_u24 v118, v115, s80, v119
	v_add_u32_e32 v118, s63, v118
	v_add_u32_e32 v119, 0x400, v118
	v_lshlrev_b32_e32 v115, 4, v115
	s_mov_b32 s75, s60
	s_branch .Lcvc_p0_m0
.Lcvc_p0_m0:
	s_mov_b32 s80, s75
	s_add_u32 s80, s80, 0x400
	s_lshr_b32 s81, s80, 7
	s_and_b32 s82, s80, 0x7f
	s_lshl_b32 s81, s81, 6
	s_lshl_b32 s82, s82, 6
	s_mul_i32 s83, s82, 0x800
	s_add_u32 s83, s83, s81
	s_lshl_b32 s83, s83, 2
	s_add_u32 s64, s24, s83
	s_addc_u32 s65, s25, 0
	s_lshl_b32 s84, s81, 13
	s_add_u32 s84, s84, s82
	s_lshl_b32 s84, s84, 1
	s_add_u32 s84, s84, 0x3900000
	s_add_u32 s76, s28, s84
	s_addc_u32 s77, s29, 0
	s_mov_b32 s70, 0x8000
	s_mov_b32 s78, 0x20000
	s_mov_b32 s72, 0x2000
	s_mov_b32 s85, 0x4000
	s_mov_b32 s79, 0
	v_mad_u32_u24 v120, v113, s72, v112
	v_mad_u32_u24 v124, v116, s85, v115

; #define LAS __attribute__((address_space(3)))
; __device__ __forceinline__ void convert_out_down(const Args& A, LAS unsigned char* lds, int vcu, int G) {
;     int tid = threadIdx.x; asm volatile("" : "+v"(tid)); const int lane = tid & 63, wave = __builtin_amdgcn_readfirstlane(tid >> 6);
;     unsigned char* ws = A.ws;
;     __syncthreads();
;     LAS float* scr = (LAS float*)(lds + wave * 16640);
;     constexpr int I_OUT0 = (D / 64) * (D / 64), I_DN0 = (FF / 64) * (D / 64);
;     for (int it = vcu * NW + wave; it < I_OUT0 + I_DN0; it += G * NW) {
;         if (it < I_OUT0) transpose_tile(A.w_out, D, D, (bf16*)(ws + WS_WOUT), A.g_ao, A.g_go, 1024, scr, it, lane);
;         else transpose_tile(A.w_down, FF, D, (bf16*)(ws + WS_WDOWN), nullptr, nullptr, 0, scr, it - I_OUT0, lane);
;     }
;     __syncthreads();
; __global__ void __launch_bounds__(NT, 2) fwd_mega(Args A) {
;     ...
;     if (vcu2 & 1) convert_out_down(A, lds, vcu2, G);
.LBB0_621:
	s_and_b64 vcc, exec, s[22:23]
	s_cbranch_vccz .LBB0_662
	s_waitcnt lgkmcnt(0)
	s_barrier
	s_lshl_b32 s0, s96, 3
	v_readlane_b32 s2, v255, 3
	s_nop 3
	s_add_i32 s60, s0, s2
	s_mov_b32 s61, s52
	s_movk_i32 s62, 0xc00
	s_cmp_ge_u32 s60, s62
	s_cbranch_scc1 .Lcvd_end
	v_readlane_b32 s63, v255, 3
	v_and_b32_e32 v122, 63, v160
	v_and_b32_e32 v112, 15, v122
	v_lshlrev_b32_e32 v112, 4, v112
	v_lshrrev_b32_e32 v113, 4, v122
	v_lshlrev_b32_e32 v114, 2, v113
	v_and_b32_e32 v115, 7, v122
	v_lshrrev_b32_e32 v116, 3, v122
	s_mulk_i32 s63, 0x4100
	s_movk_i32 s80, 0x104
	v_mad_u32_u24 v117, v113, s80, v112
	v_add_u32_e32 v117, s63, v117
	s_movk_i32 s80, 0x820
	v_lshlrev_b32_e32 v119, 2, v116
	v_mad_u32_u24 v118, v115, s80, v119
	v_add_u32_e32 v118, s63, v118
	v_add_u32_e32 v119, 0x400, v118
	v_lshlrev_b32_e32 v115, 4, v115
	s_mov_b32 s75, s60
	s_branch .Lcvd_p0_m0
